# seam barriers: L1 invalidate issued by the leader right behind its arrival atomic (overlaps the barrier wait) instead of after the release
# speedup vs baseline: 1.0069x; 1.0044x over previous
.LBB0_131:
	s_mov_b64 s[12:13], exec
	s_lshl_b32 s10, s33, 8
	v_mbcnt_lo_u32_b32 v1, s12, 0
	s_add_u32 s10, s34, s10
	v_mbcnt_hi_u32_b32 v1, s13, v1
	s_addc_u32 s11, s35, 0
	v_cmp_eq_u32_e32 vcc, 0, v1
	s_and_saveexec_b64 s[14:15], vcc
	s_cbranch_execz .LBB0_133
	s_bcnt1_i32_b64 s12, s[12:13]
	v_mov_b32_e32 v3, 0x1000
	v_mov_b32_e32 v4, s12
	global_atomic_add v3, v3, v4, s[10:11] offset:1024 sc0
	buffer_inv sc1
.LBB0_133:
	s_or_b64 exec, exec, s[14:15]
	v_cvt_f32_u32_e32 v4, v2
	s_waitcnt vmcnt(1)
	v_readfirstlane_b32 s12, v3
	v_sub_u32_e32 v3, 0, v2
	v_rcp_iflag_f32_e32 v4, v4
	v_add_u32_e32 v5, s12, v1
	v_mul_f32_e32 v4, 0x4f7ffffe, v4
	v_cvt_u32_f32_e32 v4, v4
	v_mul_lo_u32 v1, v3, v4
	v_mul_hi_u32 v1, v4, v1
	v_add_u32_e32 v1, v4, v1
	v_mul_hi_u32 v1, v5, v1
	v_mul_lo_u32 v3, v1, v2
	v_sub_u32_e32 v3, v5, v3
	v_add_u32_e32 v4, 1, v1
	v_cmp_ge_u32_e32 vcc, v3, v2
	s_nop 1
	v_cndmask_b32_e32 v1, v1, v4, vcc
	v_sub_u32_e32 v4, v3, v2
	v_cndmask_b32_e32 v3, v3, v4, vcc
	v_add_u32_e32 v4, 1, v1
	v_cmp_ge_u32_e32 vcc, v3, v2
	v_add_u32_e32 v3, 1, v5
	s_nop 0
	v_cndmask_b32_e32 v1, v1, v4, vcc
	v_mul_lo_u32 v4, v2, v1
	v_add_u32_e32 v2, v4, v2
	v_cmp_ne_u32_e32 vcc, v3, v2
	s_and_saveexec_b64 s[12:13], vcc
	s_xor_b64 s[12:13], exec, s[12:13]
	s_cbranch_execz .LBB0_147
	s_waitcnt lgkmcnt(0)
	v_mov_b32_e32 v0, 0x2000
	global_load_dword v0, v0, s[10:11] offset:1024 sc1
	s_add_u32 s18, s10, 0x2400
	s_addc_u32 s19, s11, 0
	s_waitcnt vmcnt(0)
	v_cmp_eq_u32_e32 vcc, v0, v1
	s_and_saveexec_b64 s[14:15], vcc
	s_cbranch_execz .LBB0_146
	s_add_u32 s16, s30, 0x40200
	s_addc_u32 s17, s31, 0
	s_mov_b32 s40, 1
	s_mov_b64 s[20:21], 0
	v_mov_b32_e32 v0, 0
	s_branch .LBB0_137

.LBB0_146:
	s_or_b64 exec, exec, s[14:15]
	s_waitcnt vmcnt(0)
	s_nop 0
	s_waitcnt vmcnt(0)

.LBB0_164:
	s_or_b64 exec, exec, s[12:13]
	s_mov_b64 s[12:13], exec
	v_mbcnt_lo_u32_b32 v0, s12, 0
	v_mbcnt_hi_u32_b32 v0, s13, v0
	v_cmp_eq_u32_e32 vcc, 0, v0
	s_waitcnt vmcnt(0)
	s_nop 0
	s_and_saveexec_b64 s[14:15], vcc
	s_cbranch_execz .LBB0_166
	s_bcnt1_i32_b64 s12, s[12:13]
	v_mov_b32_e32 v0, 0x2000
	v_mov_b32_e32 v1, s12
	s_nop 0

.LBB0_243:
	s_mov_b64 s[12:13], exec
	s_lshl_b32 s10, s33, 8
	v_mbcnt_lo_u32_b32 v1, s12, 0
	s_add_u32 s10, s34, s10
	v_mbcnt_hi_u32_b32 v1, s13, v1
	s_addc_u32 s11, s35, 0
	v_cmp_eq_u32_e32 vcc, 0, v1
	s_and_saveexec_b64 s[14:15], vcc
	s_cbranch_execz .LBB0_245
	s_bcnt1_i32_b64 s12, s[12:13]
	v_mov_b32_e32 v3, 0x1000
	v_mov_b32_e32 v4, s12
	global_atomic_add v3, v3, v4, s[10:11] offset:1024 sc0
	v_mov_b32_e32 v22, 1
	s_and_b32 s98, s60, 7
	s_lshl_b32 s98, s98, 8
	s_add_i32 s98, s98, 0x4000
	v_mov_b32_e32 v21, s98
	global_atomic_add v20, v21, v22, s[34:35] sc0
	s_mov_b32 s101, 1
	buffer_inv sc1

.LBB0_534:
	s_mov_b64 s[10:11], exec
	s_lshl_b32 s8, s33, 8
	v_mbcnt_lo_u32_b32 v1, s10, 0
	s_add_u32 s8, s34, s8
	v_mbcnt_hi_u32_b32 v1, s11, v1
	s_addc_u32 s9, s35, 0
	v_cmp_eq_u32_e32 vcc, 0, v1
	s_and_saveexec_b64 s[12:13], vcc
	s_cbranch_execz .LBB0_536
	s_bcnt1_i32_b64 s10, s[10:11]
	v_mov_b32_e32 v3, 0x1000
	v_mov_b32_e32 v4, s10
	global_atomic_add v3, v3, v4, s[8:9] offset:1024 sc0
	buffer_inv sc1
.LBB0_536:
	s_or_b64 exec, exec, s[12:13]
	v_cvt_f32_u32_e32 v4, v2
	s_waitcnt vmcnt(1)
	v_readfirstlane_b32 s10, v3
	v_sub_u32_e32 v3, 0, v2
	v_rcp_iflag_f32_e32 v4, v4
	v_add_u32_e32 v5, s10, v1
	v_mul_f32_e32 v4, 0x4f7ffffe, v4
	v_cvt_u32_f32_e32 v4, v4
	v_mul_lo_u32 v1, v3, v4
	v_mul_hi_u32 v1, v4, v1
	v_add_u32_e32 v1, v4, v1
	v_mul_hi_u32 v1, v5, v1
	v_mul_lo_u32 v3, v1, v2
	v_sub_u32_e32 v3, v5, v3
	v_add_u32_e32 v4, 1, v1
	v_cmp_ge_u32_e32 vcc, v3, v2
	s_nop 1
	v_cndmask_b32_e32 v1, v1, v4, vcc
	v_sub_u32_e32 v4, v3, v2
	v_cndmask_b32_e32 v3, v3, v4, vcc
	v_add_u32_e32 v4, 1, v1
	v_cmp_ge_u32_e32 vcc, v3, v2
	v_add_u32_e32 v3, 1, v5
	s_nop 0
	v_cndmask_b32_e32 v1, v1, v4, vcc
	v_mul_lo_u32 v4, v2, v1
	v_add_u32_e32 v2, v4, v2
	v_cmp_ne_u32_e32 vcc, v3, v2
	s_and_saveexec_b64 s[10:11], vcc
	s_xor_b64 s[10:11], exec, s[10:11]
	s_cbranch_execz .LBB0_550
	s_waitcnt lgkmcnt(0)
	v_mov_b32_e32 v0, 0x2000
	global_load_dword v0, v0, s[8:9] offset:1024 sc1
	s_add_u32 s16, s8, 0x2400
	s_addc_u32 s17, s9, 0
	s_waitcnt vmcnt(0)
	v_cmp_eq_u32_e32 vcc, v0, v1
	s_and_saveexec_b64 s[12:13], vcc
	s_cbranch_execz .LBB0_549
	s_add_u32 s14, s30, 0x40200
	s_addc_u32 s15, s31, 0
	s_mov_b32 s38, 1
	s_mov_b64 s[18:19], 0
	v_mov_b32_e32 v0, 0
	s_branch .LBB0_540

.LBB0_549:
	s_or_b64 exec, exec, s[12:13]
	s_waitcnt vmcnt(0)
	s_nop 0
	s_waitcnt vmcnt(0)

.LBB0_567:
	s_or_b64 exec, exec, s[10:11]
	s_mov_b64 s[10:11], exec
	v_mbcnt_lo_u32_b32 v0, s10, 0
	v_mbcnt_hi_u32_b32 v0, s11, v0
	v_cmp_eq_u32_e32 vcc, 0, v0
	s_waitcnt vmcnt(0)
	s_nop 0
	s_and_saveexec_b64 s[12:13], vcc
	s_cbranch_execz .LBB0_569
	s_bcnt1_i32_b64 s10, s[10:11]
	v_mov_b32_e32 v0, 0x2000
	v_mov_b32_e32 v1, s10
	s_nop 0

.LBB0_709:
	s_cmp_gt_i32 s89, 5
	s_cselect_b64 s[4:5], -1, 0
	s_and_b64 s[6:7], s[6:7], s[4:5]
	s_andn2_b64 vcc, exec, s[6:7]
	s_cbranch_vccnz .LBB0_763
	s_waitcnt vmcnt(0)
	s_waitcnt vmcnt(0)
	s_barrier
	s_and_saveexec_b64 s[6:7], s[26:27]
	s_cbranch_execz .LBB0_762
	s_cmp_eq_u32 s100, 0
	s_cbranch_scc1 .Lgrp_full_4
	s_and_b32 s98, s2, 63
	s_lshl_b32 s98, s98, 2
	v_mov_b32_e32 v0, s98
	v_mov_b32_e32 v1, 1
	global_atomic_add v0, v1, s[34:35]
	buffer_inv sc1
	s_mov_b32 s99, 0

.Lgrp_rel_4:
	s_nop 0
	s_waitcnt vmcnt(0)
	s_branch .LBB0_762

.LBB0_1329:
	s_cmp_gt_i32 s89, 12
	s_cselect_b64 s[4:5], -1, 0
	s_and_b64 s[6:7], s[6:7], s[4:5]
	s_andn2_b64 vcc, exec, s[6:7]
	s_cbranch_vccnz .LBB0_1383
	s_waitcnt vmcnt(0)
	s_waitcnt vmcnt(0)
	s_barrier
	s_and_saveexec_b64 s[6:7], s[26:27]
	s_cbranch_execz .LBB0_1382
	s_cmp_eq_u32 s100, 0
	s_cbranch_scc1 .Lgrp_full_11
	s_and_b32 s98, s2, 63
	s_lshl_b32 s98, s98, 2
	v_mov_b32_e32 v0, s98
	v_mov_b32_e32 v1, 1
	global_atomic_add v0, v1, s[34:35]
	buffer_inv sc1
	s_mov_b32 s99, 0

.LBB0_1348:
	s_or_b64 exec, exec, s[12:13]
	v_cvt_f32_u32_e32 v4, v2
	s_waitcnt vmcnt(1)
	v_readfirstlane_b32 s10, v3
	v_sub_u32_e32 v3, 0, v2
	v_rcp_iflag_f32_e32 v4, v4
	v_add_u32_e32 v5, s10, v1
	v_mul_f32_e32 v4, 0x4f7ffffe, v4
	v_cvt_u32_f32_e32 v4, v4
	v_mul_lo_u32 v1, v3, v4
	v_mul_hi_u32 v1, v4, v1
	v_add_u32_e32 v1, v4, v1
	v_mul_hi_u32 v1, v5, v1
	v_mul_lo_u32 v3, v1, v2
	v_sub_u32_e32 v3, v5, v3
	v_add_u32_e32 v4, 1, v1
	v_cmp_ge_u32_e32 vcc, v3, v2
	s_nop 1
	v_cndmask_b32_e32 v1, v1, v4, vcc
	v_sub_u32_e32 v4, v3, v2
	v_cndmask_b32_e32 v3, v3, v4, vcc
	v_add_u32_e32 v4, 1, v1
	v_cmp_ge_u32_e32 vcc, v3, v2
	v_add_u32_e32 v3, 1, v5
	s_nop 0
	v_cndmask_b32_e32 v1, v1, v4, vcc
	v_mul_lo_u32 v4, v2, v1
	v_add_u32_e32 v2, v4, v2
	v_cmp_ne_u32_e32 vcc, v3, v2
	s_and_saveexec_b64 s[10:11], vcc
	s_xor_b64 s[10:11], exec, s[10:11]
	s_cbranch_execz .LBB0_1362
	s_waitcnt lgkmcnt(0)
	v_mov_b32_e32 v0, 0x2000
	global_load_dword v0, v0, s[8:9] offset:1024 sc1
	s_add_u32 s16, s8, 0x2400
	s_addc_u32 s17, s9, 0
	s_waitcnt vmcnt(0)
	v_cmp_eq_u32_e32 vcc, v0, v1
	s_and_saveexec_b64 s[12:13], vcc
	s_cbranch_execz .LBB0_1361
	s_add_u32 s14, s30, 0x40200
	s_addc_u32 s15, s31, 0
	s_mov_b32 s29, 1
	s_mov_b64 s[18:19], 0
	v_mov_b32_e32 v0, 0
	s_branch .LBB0_1352
